# PROJ GEMM k-loop also rewritten with 16x16x32 bf16 MFMA (f32 acc) + permlane swap re-layout; GU as in previous version
# speedup vs baseline: 1.0198x; 1.0123x over previous
.LBB0_215:
	s_mul_hi_i32 s0, s8, 0x2aaaaaab
	s_lshr_b32 s1, s0, 31
	s_ashr_i32 s0, s0, 5
	s_add_i32 s0, s0, s1
	s_lshl_b32 s1, s0, 3
	s_sub_i32 s2, 17, s1
	s_min_u32 s2, s2, 8
	v_cvt_f32_ubyte0_e32 v0, s2
	v_rcp_iflag_f32_e32 v0, v0
	s_sub_i32 s5, 0, s2
	s_mulk_i32 s0, 0xff40
	s_add_i32 s3, s0, s8
	v_mul_f32_e32 v0, 0x4f7ffffe, v0
	v_cvt_u32_f32_e32 v0, v0
	s_abs_i32 s4, s3
	s_ashr_i32 s0, s3, 31
	v_mov_b32_e32 v181, v179
	v_readfirstlane_b32 s6, v0
	s_mul_i32 s5, s5, s6
	s_mul_hi_u32 s5, s6, s5
	s_add_i32 s6, s6, s5
	s_mul_hi_u32 s5, s4, s6
	s_mul_i32 s6, s5, s2
	s_sub_i32 s4, s4, s6
	s_add_i32 s6, s5, 1
	s_sub_i32 s7, s4, s2
	s_cmp_ge_u32 s4, s2
	s_cselect_b32 s5, s6, s5
	s_cselect_b32 s4, s7, s4
	s_add_i32 s6, s5, 1
	s_cmp_ge_u32 s4, s2
	s_cselect_b32 s4, s6, s5
	s_xor_b32 s4, s4, s0
	s_sub_i32 s0, s4, s0
	s_mul_i32 s2, s2, s0
	s_sub_i32 s2, s3, s2
	s_add_i32 s1, s1, s11
	s_add_i32 s2, s1, s2
	v_ashrrev_i32_e32 v233, 6, v181
	v_lshlrev_b32_e32 v0, 1, v233
	v_lshl_add_u32 v0, s2, 3, v0
	v_ashrrev_i32_e32 v1, 31, v0
	v_bfe_u32 v183, v181, 5, 1
	v_lshlrev_b64 v[0:1], 16, v[0:1]
	v_and_b32_e32 v231, 31, v181
	v_lshl_add_u64 v[0:1], s[64:65], 0, v[0:1]
	v_lshlrev_b32_e32 v176, 9, v183
	s_ashr_i32 s1, s0, 31
	v_lshl_add_u64 v[0:1], v[0:1], 0, v[176:177]
	v_lshlrev_b32_e32 v176, 4, v231
	v_ashrrev_i32_e32 v12, 2, v181
	s_lshl_b64 s[4:5], s[0:1], 18
	v_lshl_add_u64 v[184:185], v[0:1], 0, v[176:177]
	s_add_u32 s4, s9, s4
	v_lshlrev_b32_e32 v0, 5, v12
	s_addc_u32 s5, s10, s5
	v_ashrrev_i32_e32 v1, 31, v0
	v_lshlrev_b32_e32 v2, 4, v181
	v_lshl_add_u64 v[0:1], v[0:1], 1, s[4:5]
	v_and_b32_e32 v176, 48, v2
	v_lshl_add_u64 v[186:187], v[0:1], 0, v[176:177]
	s_movk_i32 s1, 0x2000
	v_add_co_u32_e32 v8, vcc, s1, v186
	v_mul_u32_u24_e32 v10, 40, v231
	s_nop 0
	v_addc_co_u32_e32 v9, vcc, 0, v187, vcc
	v_lshlrev_b32_e32 v11, 4, v183
	v_lshl_add_u32 v235, v10, 1, v11
	v_add_co_u32_e32 v10, vcc, s41, v184
	s_movk_i32 s3, 0x50
	s_nop 0
	v_addc_co_u32_e32 v11, vcc, 0, v185, vcc
	v_and_b32_e32 v232, 63, v181
	v_lshlrev_b32_e32 v234, 3, v181
	v_mov_b32_e32 v176, 0x800
	v_lshl_add_u64 v[188:189], v[186:187], 0, v[176:177]
	v_bfe_u32 v197, v181, 4, 1
	v_lshlrev_b32_e32 v176, 9, v183
	v_lshl_add_u32 v176, v197, 8, v176
	v_lshl_add_u64 v[184:185], v[184:185], 0, v[176:177]
	v_mov_b32_e32 v176, s41
	v_lshl_add_u64 v[186:187], v[184:185], 0, v[176:177]
	v_lshrrev_b32_e32 v235, 2, v181
	v_bfe_u32 v197, v181, 4, 2
	v_lshlrev_b32_e32 v197, 1, v197
	v_mov_b32_e32 v176, 0x78
	v_lshrrev_b32_e32 v197, v197, v176
	v_and_b32_e32 v197, 3, v197
	v_and_b32_e32 v196, 3, v181
	v_xor_b32_e32 v197, v197, v196
	v_lshlrev_b32_e32 v197, 4, v197
	v_lshl_add_u32 v235, v235, 6, v197
	v_bfe_u32 v197, v181, 2, 2
	v_lshlrev_b32_e32 v197, 1, v197
	v_lshrrev_b32_e32 v197, v197, v176
	v_and_b32_e32 v197, 3, v197
	v_bfe_u32 v196, v181, 4, 2
	v_xor_b32_e32 v197, v197, v196
	v_lshlrev_b32_e32 v197, 4, v197
	v_and_b32_e32 v196, 15, v181
	v_lshl_add_u32 v196, v196, 6, v197
	s_mov_b32 s96, 0
	v_lshl_add_u64 v[166:167], v[188:189], 0, s[96:97]
	global_load_dwordx4 v[160:163], v[166:167], off offset:-2048
	global_load_dwordx4 v[164:167], v[166:167], off offset:2048
	v_lshl_add_u64 v[198:199], v[184:185], 0, s[96:97]
	v_lshl_add_u64 v[200:201], v[186:187], 0, s[96:97]
	global_load_dwordx4 v[128:131], v[198:199], off
	global_load_dwordx4 v[132:135], v[198:199], off offset:256
	global_load_dwordx4 v[136:139], v[200:201], off
	global_load_dwordx4 v[140:143], v[200:201], off offset:256
	s_movk_i32 s96, 0x2000
	v_lshl_add_u64 v[174:175], v[188:189], 0, s[96:97]
	global_load_dwordx4 v[168:171], v[174:175], off offset:-2048
	global_load_dwordx4 v[172:175], v[174:175], off offset:2048
	s_movk_i32 s96, 0x800
	v_lshl_add_u64 v[198:199], v[184:185], 0, s[96:97]
	v_lshl_add_u64 v[200:201], v[186:187], 0, s[96:97]
	global_load_dwordx4 v[144:147], v[198:199], off
	global_load_dwordx4 v[148:151], v[198:199], off offset:256
	global_load_dwordx4 v[152:155], v[200:201], off
	global_load_dwordx4 v[156:159], v[200:201], off offset:256
	v_mov_b32_e32 v0, 0
	v_mov_b32_e32 v1, 0
	v_mov_b32_e32 v2, 0
	v_mov_b32_e32 v3, 0
	v_mov_b32_e32 v4, 0
	v_mov_b32_e32 v5, 0
	v_mov_b32_e32 v6, 0
	v_mov_b32_e32 v7, 0
	v_mov_b32_e32 v8, 0
	v_mov_b32_e32 v9, 0
	v_mov_b32_e32 v10, 0
	v_mov_b32_e32 v11, 0
	v_mov_b32_e32 v12, 0
	v_mov_b32_e32 v13, 0
	v_mov_b32_e32 v14, 0
	v_mov_b32_e32 v15, 0
	v_mov_b32_e32 v16, 0
	v_mov_b32_e32 v17, 0
	v_mov_b32_e32 v18, 0
	v_mov_b32_e32 v19, 0
	v_mov_b32_e32 v20, 0
	v_mov_b32_e32 v21, 0
	v_mov_b32_e32 v22, 0
	v_mov_b32_e32 v23, 0
	v_mov_b32_e32 v24, 0
	v_mov_b32_e32 v25, 0
	v_mov_b32_e32 v26, 0
	v_mov_b32_e32 v27, 0
	v_mov_b32_e32 v28, 0
	v_mov_b32_e32 v29, 0
	v_mov_b32_e32 v30, 0
	v_mov_b32_e32 v31, 0
	v_mov_b32_e32 v32, 0
	v_mov_b32_e32 v33, 0
	v_mov_b32_e32 v34, 0
	v_mov_b32_e32 v35, 0
	v_mov_b32_e32 v36, 0
	v_mov_b32_e32 v37, 0
	v_mov_b32_e32 v38, 0
	v_mov_b32_e32 v39, 0
	v_mov_b32_e32 v40, 0
	v_mov_b32_e32 v41, 0
	v_mov_b32_e32 v42, 0
	v_mov_b32_e32 v43, 0
	v_mov_b32_e32 v44, 0
	v_mov_b32_e32 v45, 0
	v_mov_b32_e32 v46, 0
	v_mov_b32_e32 v47, 0
	v_mov_b32_e32 v48, 0
	v_mov_b32_e32 v49, 0
	v_mov_b32_e32 v50, 0
	v_mov_b32_e32 v51, 0
	v_mov_b32_e32 v52, 0
	v_mov_b32_e32 v53, 0
	v_mov_b32_e32 v54, 0
	v_mov_b32_e32 v55, 0
	v_mov_b32_e32 v56, 0
	v_mov_b32_e32 v57, 0
	v_mov_b32_e32 v58, 0
	v_mov_b32_e32 v59, 0
	v_mov_b32_e32 v60, 0
	v_mov_b32_e32 v61, 0
	v_mov_b32_e32 v62, 0
	v_mov_b32_e32 v63, 0
	v_mov_b32_e32 v64, 0
	v_mov_b32_e32 v65, 0
	v_mov_b32_e32 v66, 0
	v_mov_b32_e32 v67, 0
	v_mov_b32_e32 v68, 0
	v_mov_b32_e32 v69, 0
	v_mov_b32_e32 v70, 0
	v_mov_b32_e32 v71, 0
	v_mov_b32_e32 v72, 0
	v_mov_b32_e32 v73, 0
	v_mov_b32_e32 v74, 0
	v_mov_b32_e32 v75, 0
	v_mov_b32_e32 v76, 0
	v_mov_b32_e32 v77, 0
	v_mov_b32_e32 v78, 0
	v_mov_b32_e32 v79, 0
	v_mov_b32_e32 v80, 0
	v_mov_b32_e32 v81, 0
	v_mov_b32_e32 v82, 0
	v_mov_b32_e32 v83, 0
	v_mov_b32_e32 v84, 0
	v_mov_b32_e32 v85, 0
	v_mov_b32_e32 v86, 0
	v_mov_b32_e32 v87, 0
	v_mov_b32_e32 v88, 0
	v_mov_b32_e32 v89, 0
	v_mov_b32_e32 v90, 0
	v_mov_b32_e32 v91, 0
	v_mov_b32_e32 v92, 0
	v_mov_b32_e32 v93, 0
	v_mov_b32_e32 v94, 0
	v_mov_b32_e32 v95, 0
	v_mov_b32_e32 v96, 0
	v_mov_b32_e32 v97, 0
	v_mov_b32_e32 v98, 0
	v_mov_b32_e32 v99, 0
	v_mov_b32_e32 v100, 0
	v_mov_b32_e32 v101, 0
	v_mov_b32_e32 v102, 0
	v_mov_b32_e32 v103, 0
	v_mov_b32_e32 v104, 0
	v_mov_b32_e32 v105, 0
	v_mov_b32_e32 v106, 0
	v_mov_b32_e32 v107, 0
	v_mov_b32_e32 v108, 0
	v_mov_b32_e32 v109, 0
	v_mov_b32_e32 v110, 0
	v_mov_b32_e32 v111, 0
	v_mov_b32_e32 v112, 0
	v_mov_b32_e32 v113, 0
	v_mov_b32_e32 v114, 0
	v_mov_b32_e32 v115, 0
	v_mov_b32_e32 v116, 0
	v_mov_b32_e32 v117, 0
	v_mov_b32_e32 v118, 0
	v_mov_b32_e32 v119, 0
	v_mov_b32_e32 v120, 0
	v_mov_b32_e32 v121, 0
	v_mov_b32_e32 v122, 0
	v_mov_b32_e32 v123, 0
	v_mov_b32_e32 v124, 0
	v_mov_b32_e32 v125, 0
	v_mov_b32_e32 v126, 0
	v_mov_b32_e32 v127, 0
	s_mov_b32 s1, 0
	s_waitcnt vmcnt(10)
	ds_write_b128 v235, v[160:163]
	ds_write_b128 v235, v[164:167] offset:4096
	s_waitcnt lgkmcnt(0)
	s_barrier
.Lg16_proj_k:
	s_add_i32 s3, s1, 2
	s_min_u32 s4, s3, 30
	s_lshl_b32 s96, s4, 13
	v_lshl_add_u64 v[166:167], v[188:189], 0, s[96:97]
	global_load_dwordx4 v[160:163], v[166:167], off offset:-2048
	global_load_dwordx4 v[164:167], v[166:167], off offset:2048
	ds_read_b128 v[236:239], v196 offset:0
	ds_read_b128 v[240:243], v196 offset:1024
	ds_read_b128 v[244:247], v196 offset:2048
	ds_read_b128 v[248:251], v196 offset:3072
	s_lshl_b32 s96, s4, 11
	v_lshl_add_u64 v[198:199], v[184:185], 0, s[96:97]
	v_lshl_add_u64 v[200:201], v[186:187], 0, s[96:97]
	s_waitcnt vmcnt(8) lgkmcnt(3)
	v_mfma_f32_16x16x32_bf16 v[16:19], v[128:131], v[236:239], v[16:19]
	v_mfma_f32_16x16x32_bf16 v[24:27], v[132:135], v[236:239], v[24:27]
	v_mfma_f32_16x16x32_bf16 v[0:3], v[136:139], v[236:239], v[0:3]
	v_mfma_f32_16x16x32_bf16 v[8:11], v[140:143], v[236:239], v[8:11]
	ds_read_b128 v[236:239], v196 offset:4096
	s_waitcnt lgkmcnt(3)
	v_mfma_f32_16x16x32_bf16 v[20:23], v[128:131], v[240:243], v[20:23]
	v_mfma_f32_16x16x32_bf16 v[28:31], v[132:135], v[240:243], v[28:31]
	v_mfma_f32_16x16x32_bf16 v[4:7], v[136:139], v[240:243], v[4:7]
	v_mfma_f32_16x16x32_bf16 v[12:15], v[140:143], v[240:243], v[12:15]
	ds_read_b128 v[240:243], v196 offset:5120
	s_waitcnt lgkmcnt(3)
	v_mfma_f32_16x16x32_bf16 v[112:115], v[128:131], v[244:247], v[112:115]
	v_mfma_f32_16x16x32_bf16 v[120:123], v[132:135], v[244:247], v[120:123]
	v_mfma_f32_16x16x32_bf16 v[96:99], v[136:139], v[244:247], v[96:99]
	v_mfma_f32_16x16x32_bf16 v[104:107], v[140:143], v[244:247], v[104:107]
	ds_read_b128 v[244:247], v196 offset:6144
	s_waitcnt lgkmcnt(3)
	v_mfma_f32_16x16x32_bf16 v[116:119], v[128:131], v[248:251], v[116:119]
	v_mfma_f32_16x16x32_bf16 v[124:127], v[132:135], v[248:251], v[124:127]
	v_mfma_f32_16x16x32_bf16 v[100:103], v[136:139], v[248:251], v[100:103]
	v_mfma_f32_16x16x32_bf16 v[108:111], v[140:143], v[248:251], v[108:111]
	ds_read_b128 v[248:251], v196 offset:7168
	s_waitcnt vmcnt(6)
	ds_write_b128 v235, v[168:171] offset:8192
	ds_write_b128 v235, v[172:175] offset:12288
	s_waitcnt lgkmcnt(5)
	v_mfma_f32_16x16x32_bf16 v[80:83], v[128:131], v[236:239], v[80:83]
	v_mfma_f32_16x16x32_bf16 v[88:91], v[132:135], v[236:239], v[88:91]
	v_mfma_f32_16x16x32_bf16 v[48:51], v[136:139], v[236:239], v[48:51]
	v_mfma_f32_16x16x32_bf16 v[56:59], v[140:143], v[236:239], v[56:59]
	s_waitcnt lgkmcnt(4)
	v_mfma_f32_16x16x32_bf16 v[84:87], v[128:131], v[240:243], v[84:87]
	v_mfma_f32_16x16x32_bf16 v[92:95], v[132:135], v[240:243], v[92:95]
	v_mfma_f32_16x16x32_bf16 v[52:55], v[136:139], v[240:243], v[52:55]
	v_mfma_f32_16x16x32_bf16 v[60:63], v[140:143], v[240:243], v[60:63]
	s_waitcnt lgkmcnt(3)
	v_mfma_f32_16x16x32_bf16 v[64:67], v[128:131], v[244:247], v[64:67]
	v_mfma_f32_16x16x32_bf16 v[72:75], v[132:135], v[244:247], v[72:75]
	v_mfma_f32_16x16x32_bf16 v[32:35], v[136:139], v[244:247], v[32:35]
	v_mfma_f32_16x16x32_bf16 v[40:43], v[140:143], v[244:247], v[40:43]
	s_waitcnt lgkmcnt(2)
	v_mfma_f32_16x16x32_bf16 v[68:71], v[128:131], v[248:251], v[68:71]
	v_mfma_f32_16x16x32_bf16 v[76:79], v[132:135], v[248:251], v[76:79]
	v_mfma_f32_16x16x32_bf16 v[36:39], v[136:139], v[248:251], v[36:39]
	v_mfma_f32_16x16x32_bf16 v[44:47], v[140:143], v[248:251], v[44:47]
	global_load_dwordx4 v[128:131], v[198:199], off
	global_load_dwordx4 v[132:135], v[198:199], off offset:256
	global_load_dwordx4 v[136:139], v[200:201], off
	global_load_dwordx4 v[140:143], v[200:201], off offset:256
	s_waitcnt lgkmcnt(0)
	s_barrier
	s_add_i32 s3, s1, 3
	s_min_u32 s4, s3, 31
	s_lshl_b32 s96, s4, 13
	v_lshl_add_u64 v[174:175], v[188:189], 0, s[96:97]
	global_load_dwordx4 v[168:171], v[174:175], off offset:-2048
	global_load_dwordx4 v[172:175], v[174:175], off offset:2048
	ds_read_b128 v[236:239], v196 offset:8192
	ds_read_b128 v[240:243], v196 offset:9216
	ds_read_b128 v[244:247], v196 offset:10240
	ds_read_b128 v[248:251], v196 offset:11264
	s_lshl_b32 s96, s4, 11
	v_lshl_add_u64 v[198:199], v[184:185], 0, s[96:97]
	v_lshl_add_u64 v[200:201], v[186:187], 0, s[96:97]
	s_waitcnt vmcnt(8) lgkmcnt(3)
	v_mfma_f32_16x16x32_bf16 v[16:19], v[144:147], v[236:239], v[16:19]
	v_mfma_f32_16x16x32_bf16 v[24:27], v[148:151], v[236:239], v[24:27]
	v_mfma_f32_16x16x32_bf16 v[0:3], v[152:155], v[236:239], v[0:3]
	v_mfma_f32_16x16x32_bf16 v[8:11], v[156:159], v[236:239], v[8:11]
	ds_read_b128 v[236:239], v196 offset:12288
	s_waitcnt lgkmcnt(3)
	v_mfma_f32_16x16x32_bf16 v[20:23], v[144:147], v[240:243], v[20:23]
	v_mfma_f32_16x16x32_bf16 v[28:31], v[148:151], v[240:243], v[28:31]
	v_mfma_f32_16x16x32_bf16 v[4:7], v[152:155], v[240:243], v[4:7]
	v_mfma_f32_16x16x32_bf16 v[12:15], v[156:159], v[240:243], v[12:15]
	ds_read_b128 v[240:243], v196 offset:13312
	s_waitcnt lgkmcnt(3)
	v_mfma_f32_16x16x32_bf16 v[112:115], v[144:147], v[244:247], v[112:115]
	v_mfma_f32_16x16x32_bf16 v[120:123], v[148:151], v[244:247], v[120:123]
	v_mfma_f32_16x16x32_bf16 v[96:99], v[152:155], v[244:247], v[96:99]
	v_mfma_f32_16x16x32_bf16 v[104:107], v[156:159], v[244:247], v[104:107]
	ds_read_b128 v[244:247], v196 offset:14336
	s_waitcnt lgkmcnt(3)
	v_mfma_f32_16x16x32_bf16 v[116:119], v[144:147], v[248:251], v[116:119]
	v_mfma_f32_16x16x32_bf16 v[124:127], v[148:151], v[248:251], v[124:127]
	v_mfma_f32_16x16x32_bf16 v[100:103], v[152:155], v[248:251], v[100:103]
	v_mfma_f32_16x16x32_bf16 v[108:111], v[156:159], v[248:251], v[108:111]
	ds_read_b128 v[248:251], v196 offset:15360
	s_waitcnt vmcnt(6)
	ds_write_b128 v235, v[160:163] offset:0
	ds_write_b128 v235, v[164:167] offset:4096
	s_waitcnt lgkmcnt(5)
	v_mfma_f32_16x16x32_bf16 v[80:83], v[144:147], v[236:239], v[80:83]
	v_mfma_f32_16x16x32_bf16 v[88:91], v[148:151], v[236:239], v[88:91]
	v_mfma_f32_16x16x32_bf16 v[48:51], v[152:155], v[236:239], v[48:51]
	v_mfma_f32_16x16x32_bf16 v[56:59], v[156:159], v[236:239], v[56:59]
	s_waitcnt lgkmcnt(4)
	v_mfma_f32_16x16x32_bf16 v[84:87], v[144:147], v[240:243], v[84:87]
	v_mfma_f32_16x16x32_bf16 v[92:95], v[148:151], v[240:243], v[92:95]
	v_mfma_f32_16x16x32_bf16 v[52:55], v[152:155], v[240:243], v[52:55]
	v_mfma_f32_16x16x32_bf16 v[60:63], v[156:159], v[240:243], v[60:63]
	s_waitcnt lgkmcnt(3)
	v_mfma_f32_16x16x32_bf16 v[64:67], v[144:147], v[244:247], v[64:67]
	v_mfma_f32_16x16x32_bf16 v[72:75], v[148:151], v[244:247], v[72:75]
	v_mfma_f32_16x16x32_bf16 v[32:35], v[152:155], v[244:247], v[32:35]
	v_mfma_f32_16x16x32_bf16 v[40:43], v[156:159], v[244:247], v[40:43]
	s_waitcnt lgkmcnt(2)
	v_mfma_f32_16x16x32_bf16 v[68:71], v[144:147], v[248:251], v[68:71]
	v_mfma_f32_16x16x32_bf16 v[76:79], v[148:151], v[248:251], v[76:79]
	v_mfma_f32_16x16x32_bf16 v[36:39], v[152:155], v[248:251], v[36:39]
	v_mfma_f32_16x16x32_bf16 v[44:47], v[156:159], v[248:251], v[44:47]
	global_load_dwordx4 v[144:147], v[198:199], off
	global_load_dwordx4 v[148:151], v[198:199], off offset:256
	global_load_dwordx4 v[152:155], v[200:201], off
	global_load_dwordx4 v[156:159], v[200:201], off offset:256
	s_add_i32 s1, s1, 2
	s_cmp_lt_u32 s1, 32
	s_waitcnt lgkmcnt(0)
	s_barrier
	s_cbranch_scc1 .Lg16_proj_k
	s_nop 7
	v_permlane16_swap_b32_e32 v16, v20
	v_permlane16_swap_b32_e32 v17, v21
	v_permlane16_swap_b32_e32 v18, v22
	v_permlane16_swap_b32_e32 v19, v23
	v_permlane16_swap_b32_e32 v24, v28
	v_permlane16_swap_b32_e32 v25, v29
	v_permlane16_swap_b32_e32 v26, v30
	v_permlane16_swap_b32_e32 v27, v31
	v_permlane16_swap_b32_e32 v112, v116
	v_permlane16_swap_b32_e32 v113, v117
	v_permlane16_swap_b32_e32 v114, v118
	v_permlane16_swap_b32_e32 v115, v119
	v_permlane16_swap_b32_e32 v120, v124
	v_permlane16_swap_b32_e32 v121, v125
	v_permlane16_swap_b32_e32 v122, v126
	v_permlane16_swap_b32_e32 v123, v127
	v_permlane16_swap_b32_e32 v80, v84
	v_permlane16_swap_b32_e32 v81, v85
	v_permlane16_swap_b32_e32 v82, v86
	v_permlane16_swap_b32_e32 v83, v87
	v_permlane16_swap_b32_e32 v88, v92
	v_permlane16_swap_b32_e32 v89, v93
	v_permlane16_swap_b32_e32 v90, v94
	v_permlane16_swap_b32_e32 v91, v95
	v_permlane16_swap_b32_e32 v64, v68
	v_permlane16_swap_b32_e32 v65, v69
	v_permlane16_swap_b32_e32 v66, v70
	v_permlane16_swap_b32_e32 v67, v71
	v_permlane16_swap_b32_e32 v72, v76
	v_permlane16_swap_b32_e32 v73, v77
	v_permlane16_swap_b32_e32 v74, v78
	v_permlane16_swap_b32_e32 v75, v79
	v_permlane16_swap_b32_e32 v0, v4
	v_permlane16_swap_b32_e32 v1, v5
	v_permlane16_swap_b32_e32 v2, v6
	v_permlane16_swap_b32_e32 v3, v7
	v_permlane16_swap_b32_e32 v8, v12
	v_permlane16_swap_b32_e32 v9, v13
	v_permlane16_swap_b32_e32 v10, v14
	v_permlane16_swap_b32_e32 v11, v15
	v_permlane16_swap_b32_e32 v96, v100
	v_permlane16_swap_b32_e32 v97, v101
	v_permlane16_swap_b32_e32 v98, v102
	v_permlane16_swap_b32_e32 v99, v103
	v_permlane16_swap_b32_e32 v104, v108
	v_permlane16_swap_b32_e32 v105, v109
	v_permlane16_swap_b32_e32 v106, v110
	v_permlane16_swap_b32_e32 v107, v111
	v_permlane16_swap_b32_e32 v48, v52
	v_permlane16_swap_b32_e32 v49, v53
	v_permlane16_swap_b32_e32 v50, v54
	v_permlane16_swap_b32_e32 v51, v55
	v_permlane16_swap_b32_e32 v56, v60
	v_permlane16_swap_b32_e32 v57, v61
	v_permlane16_swap_b32_e32 v58, v62
	v_permlane16_swap_b32_e32 v59, v63
	v_permlane16_swap_b32_e32 v32, v36
	v_permlane16_swap_b32_e32 v33, v37
	v_permlane16_swap_b32_e32 v34, v38
	v_permlane16_swap_b32_e32 v35, v39
	v_permlane16_swap_b32_e32 v40, v44
	v_permlane16_swap_b32_e32 v41, v45
	v_permlane16_swap_b32_e32 v42, v46
	v_permlane16_swap_b32_e32 v43, v47
	v_permlane32_swap_b32_e32 v16, v20
	v_permlane32_swap_b32_e32 v17, v21
	v_permlane32_swap_b32_e32 v18, v22
	v_permlane32_swap_b32_e32 v19, v23
	v_permlane32_swap_b32_e32 v24, v28
	v_permlane32_swap_b32_e32 v25, v29
	v_permlane32_swap_b32_e32 v26, v30
	v_permlane32_swap_b32_e32 v27, v31
	v_permlane32_swap_b32_e32 v112, v116
	v_permlane32_swap_b32_e32 v113, v117
	v_permlane32_swap_b32_e32 v114, v118
	v_permlane32_swap_b32_e32 v115, v119
	v_permlane32_swap_b32_e32 v120, v124
	v_permlane32_swap_b32_e32 v121, v125
	v_permlane32_swap_b32_e32 v122, v126
	v_permlane32_swap_b32_e32 v123, v127
	v_permlane32_swap_b32_e32 v80, v84
	v_permlane32_swap_b32_e32 v81, v85
	v_permlane32_swap_b32_e32 v82, v86
	v_permlane32_swap_b32_e32 v83, v87
	v_permlane32_swap_b32_e32 v88, v92
	v_permlane32_swap_b32_e32 v89, v93
	v_permlane32_swap_b32_e32 v90, v94
	v_permlane32_swap_b32_e32 v91, v95
	v_permlane32_swap_b32_e32 v64, v68
	v_permlane32_swap_b32_e32 v65, v69
	v_permlane32_swap_b32_e32 v66, v70
	v_permlane32_swap_b32_e32 v67, v71
	v_permlane32_swap_b32_e32 v72, v76
	v_permlane32_swap_b32_e32 v73, v77
	v_permlane32_swap_b32_e32 v74, v78
	v_permlane32_swap_b32_e32 v75, v79
	v_permlane32_swap_b32_e32 v0, v4
	v_permlane32_swap_b32_e32 v1, v5
	v_permlane32_swap_b32_e32 v2, v6
	v_permlane32_swap_b32_e32 v3, v7
	v_permlane32_swap_b32_e32 v8, v12
	v_permlane32_swap_b32_e32 v9, v13
	v_permlane32_swap_b32_e32 v10, v14
	v_permlane32_swap_b32_e32 v11, v15
	v_permlane32_swap_b32_e32 v96, v100
	v_permlane32_swap_b32_e32 v97, v101
	v_permlane32_swap_b32_e32 v98, v102
	v_permlane32_swap_b32_e32 v99, v103
	v_permlane32_swap_b32_e32 v104, v108
	v_permlane32_swap_b32_e32 v105, v109
	v_permlane32_swap_b32_e32 v106, v110
	v_permlane32_swap_b32_e32 v107, v111
	v_permlane32_swap_b32_e32 v48, v52
	v_permlane32_swap_b32_e32 v49, v53
	v_permlane32_swap_b32_e32 v50, v54
	v_permlane32_swap_b32_e32 v51, v55
	v_permlane32_swap_b32_e32 v56, v60
	v_permlane32_swap_b32_e32 v57, v61
	v_permlane32_swap_b32_e32 v58, v62
	v_permlane32_swap_b32_e32 v59, v63
	v_permlane32_swap_b32_e32 v32, v36
	v_permlane32_swap_b32_e32 v33, v37
	v_permlane32_swap_b32_e32 v34, v38
	v_permlane32_swap_b32_e32 v35, v39
	v_permlane32_swap_b32_e32 v40, v44
	v_permlane32_swap_b32_e32 v41, v45
	v_permlane32_swap_b32_e32 v42, v46
	v_permlane32_swap_b32_e32 v43, v47
	s_waitcnt vmcnt(0)
	s_lshl_b32 s12, s2, 8
	s_cmp_eq_u32 s0, 23
	s_mov_b64 s[2:3], -1
	s_cbranch_scc1 .LBB0_347
	s_movk_i32 s1, 0x2400
	s_waitcnt vmcnt(6)
	v_and_b32_e32 v130, 0xffffffc0, v181
	s_cmp_gt_i32 s0, 10
	v_mul_lo_u32 v129, v233, s1
	v_and_b32_e32 v128, 56, v234
	v_add_u32_e32 v131, s12, v130
	s_cselect_b64 s[2:3], -1, 0
	s_cmp_gt_u32 s0, 19
	v_mul_u32_u24_e32 v130, 0x120, v183
	s_waitcnt vmcnt(0)
	v_lshl_or_b32 v132, v128, 1, v129
	v_lshl_or_b32 v128, s0, 7, v128
	s_cselect_b64 s[0:1], -1, 0
	v_lshl_add_u32 v129, v130, 1, v129
	v_lshl_or_b32 v130, v231, 1, v129
	v_cvt_pk_bf16_f32 v112, v112, s0
	ds_write_b16 v130, v112 offset:64
	v_cvt_pk_bf16_f32 v112, v17, s0
	v_cvt_pk_bf16_f32 v96, v96, s0
	ds_write_b16 v130, v112 offset:144
	v_cvt_pk_bf16_f32 v112, v113, s0
	ds_write_b16 v130, v96 offset:4672
	v_cvt_pk_bf16_f32 v96, v1, s0
	ds_write_b16 v130, v112 offset:208
	v_cvt_pk_bf16_f32 v112, v18, s0
	ds_write_b16 v130, v96 offset:4752
	v_cvt_pk_bf16_f32 v96, v97, s0
	ds_write_b16 v130, v112 offset:288
	v_cvt_pk_bf16_f32 v112, v114, s0
	ds_write_b16 v130, v96 offset:4816
	v_cvt_pk_bf16_f32 v96, v2, s0
	ds_write_b16 v130, v112 offset:352
	v_cvt_pk_bf16_f32 v112, v19, s0
	ds_write_b16 v130, v96 offset:4896
	v_cvt_pk_bf16_f32 v96, v98, s0
	ds_write_b16 v130, v112 offset:432
	v_cvt_pk_bf16_f32 v112, v115, s0
	ds_write_b16 v130, v96 offset:4960
	v_cvt_pk_bf16_f32 v96, v3, s0
	ds_write_b16 v130, v112 offset:496
	v_cvt_pk_bf16_f32 v112, v20, s0
	ds_write_b16 v130, v96 offset:5040
	v_cvt_pk_bf16_f32 v96, v99, s0
	ds_write_b16 v130, v112 offset:1152
	v_cvt_pk_bf16_f32 v112, v116, s0
	ds_write_b16 v130, v96 offset:5104
	v_cvt_pk_bf16_f32 v96, v4, s0
	ds_write_b16 v130, v112 offset:1216
	v_cvt_pk_bf16_f32 v112, v21, s0
	ds_write_b16 v130, v96 offset:5760
	v_cvt_pk_bf16_f32 v96, v100, s0
	ds_write_b16 v130, v112 offset:1296
	v_cvt_pk_bf16_f32 v112, v117, s0
	ds_write_b16 v130, v96 offset:5824
	v_cvt_pk_bf16_f32 v96, v5, s0
	ds_write_b16 v130, v112 offset:1360
	v_cvt_pk_bf16_f32 v112, v22, s0
	ds_write_b16 v130, v96 offset:5904
	v_cvt_pk_bf16_f32 v96, v101, s0
	ds_write_b16 v130, v112 offset:1440
	v_cvt_pk_bf16_f32 v112, v118, s0
	ds_write_b16 v130, v96 offset:5968
	v_cvt_pk_bf16_f32 v96, v6, s0
	ds_write_b16 v130, v112 offset:1504
	v_cvt_pk_bf16_f32 v112, v23, s0
	ds_write_b16 v130, v96 offset:6048
	v_cvt_pk_bf16_f32 v96, v102, s0
	ds_write_b16 v130, v112 offset:1584
	v_cvt_pk_bf16_f32 v112, v119, s0
	ds_write_b16 v130, v96 offset:6112
	v_cvt_pk_bf16_f32 v96, v7, s0
	ds_write_b16 v130, v112 offset:1648
	v_cvt_pk_bf16_f32 v112, v24, s0
	ds_write_b16 v130, v96 offset:6192
	v_cvt_pk_bf16_f32 v96, v103, s0
	ds_write_b16 v130, v112 offset:2304
	v_cvt_pk_bf16_f32 v112, v120, s0
	ds_write_b16 v130, v96 offset:6256
	v_cvt_pk_bf16_f32 v96, v8, s0
	ds_write_b16 v130, v112 offset:2368
	v_cvt_pk_bf16_f32 v112, v25, s0
	ds_write_b16 v130, v96 offset:6912
	v_cvt_pk_bf16_f32 v96, v104, s0
	ds_write_b16 v130, v112 offset:2448
	v_cvt_pk_bf16_f32 v112, v121, s0
	ds_write_b16 v130, v96 offset:6976
	v_cvt_pk_bf16_f32 v96, v9, s0
	ds_write_b16 v130, v112 offset:2512
	v_cvt_pk_bf16_f32 v112, v26, s0
	ds_write_b16 v130, v96 offset:7056
	v_cvt_pk_bf16_f32 v96, v105, s0
	ds_write_b16 v130, v112 offset:2592
	v_cvt_pk_bf16_f32 v112, v122, s0
	ds_write_b16 v130, v96 offset:7120
	v_cvt_pk_bf16_f32 v96, v10, s0
	ds_write_b16 v130, v112 offset:2656
	v_cvt_pk_bf16_f32 v112, v27, s0
	ds_write_b16 v130, v96 offset:7200
	v_cvt_pk_bf16_f32 v96, v106, s0
	ds_write_b16 v130, v112 offset:2736
	v_cvt_pk_bf16_f32 v112, v123, s0
	ds_write_b16 v130, v96 offset:7264
	v_cvt_pk_bf16_f32 v96, v11, s0
	ds_write_b16 v130, v112 offset:2800
	v_cvt_pk_bf16_f32 v112, v28, s0
	ds_write_b16 v130, v96 offset:7344
	v_cvt_pk_bf16_f32 v96, v107, s0
	ds_write_b16 v130, v112 offset:3456
	v_cvt_pk_bf16_f32 v112, v124, s0
	ds_write_b16 v130, v96 offset:7408
	v_cvt_pk_bf16_f32 v96, v12, s0
	ds_write_b16 v130, v112 offset:3520
	v_cvt_pk_bf16_f32 v112, v29, s0
	ds_write_b16 v130, v96 offset:8064
	v_cvt_pk_bf16_f32 v96, v108, s0
	ds_write_b16 v130, v112 offset:3600
	v_cvt_pk_bf16_f32 v112, v125, s0
	ds_write_b16 v130, v96 offset:8128
	v_cvt_pk_bf16_f32 v96, v13, s0
	ds_write_b16 v130, v112 offset:3664
	v_cvt_pk_bf16_f32 v112, v30, s0
	ds_write_b16 v130, v96 offset:8208
	v_cvt_pk_bf16_f32 v96, v109, s0
	ds_write_b16 v130, v112 offset:3744
	v_cvt_pk_bf16_f32 v112, v126, s0
	ds_write_b16 v130, v96 offset:8272
	v_cvt_pk_bf16_f32 v96, v14, s0
	ds_write_b16 v130, v112 offset:3808
	v_cvt_pk_bf16_f32 v112, v31, s0
	ds_write_b16 v130, v96 offset:8352
	v_cvt_pk_bf16_f32 v96, v110, s0
	ds_write_b16 v130, v112 offset:3888
	v_cvt_pk_bf16_f32 v112, v127, s0
	ds_write_b16 v130, v96 offset:8416
	v_cvt_pk_bf16_f32 v96, v15, s0
	v_cvt_pk_bf16_f32 v133, v16, s0
	ds_write_b16 v130, v112 offset:3952
	v_cvt_pk_bf16_f32 v112, v0, s0
	ds_write_b16 v130, v96 offset:8496
	v_cvt_pk_bf16_f32 v96, v111, s0
	ds_write_b16 v130, v133
	ds_write_b16 v130, v112 offset:4608
	ds_write_b16 v130, v96 offset:8560
	v_lshrrev_b32_e32 v109, 3, v232
	s_waitcnt lgkmcnt(0)
	v_mad_u32_u24 v96, v109, s42, v132
	ds_read_b128 v[96:99], v96
	v_mov_b32_e32 v176, v128
	v_or_b32_e32 v110, v131, v109
	s_mov_b64 s[4:5], -1
	s_and_b64 vcc, exec, s[2:3]
	s_cbranch_vccz .LBB0_224
	s_and_b64 vcc, exec, s[0:1]
	s_cbranch_vccz .LBB0_221
	v_readlane_b32 s16, v254, 15
	v_readlane_b32 s18, v254, 17
	v_readlane_b32 s19, v254, 18
	v_readlane_b32 s17, v254, 16
	v_readlane_b32 s20, v254, 19
	v_mov_b64_e32 v[100:101], s[18:19]
	v_mad_i64_i32 v[100:101], s[4:5], v110, s89, v[100:101]
	s_movk_i32 s4, 0xec00
	v_lshl_add_u64 v[100:101], v[176:177], 1, v[100:101]
	s_mov_b32 s5, -1
	v_readlane_b32 s21, v254, 20
	v_readlane_b32 s22, v254, 21
	v_readlane_b32 s23, v254, 22
	v_readlane_b32 s24, v254, 23
	v_readlane_b32 s25, v254, 24
	v_readlane_b32 s26, v254, 25
	v_readlane_b32 s27, v254, 26
	v_readlane_b32 s28, v254, 27
	v_readlane_b32 s29, v254, 28
	v_readlane_b32 s30, v254, 29
	v_readlane_b32 s31, v254, 30
	v_lshl_add_u64 v[100:101], v[100:101], 0, s[4:5]
	s_mov_b64 s[4:5], 0

.Lg16_gu_k:
	s_add_i32 s8, s1, 2
	s_min_u32 s9, s8, 30
	s_lshl_b32 s96, s9, 13
	v_lshl_add_u64 v[166:167], v[188:189], 0, s[96:97]
	global_load_dwordx4 v[160:163], v[166:167], off offset:-2048
	global_load_dwordx4 v[164:167], v[166:167], off offset:2048
	ds_read_b128 v[196:199], v246 offset:0
	ds_read_b128 v[200:203], v246 offset:1024
	ds_read_b128 v[204:207], v246 offset:2048
	ds_read_b128 v[242:245], v246 offset:3072
	s_lshl_b32 s96, s9, 11
	v_lshl_add_u64 v[248:249], v[184:185], 0, s[96:97]
	v_lshl_add_u64 v[250:251], v[186:187], 0, s[96:97]
	s_waitcnt vmcnt(8) lgkmcnt(3)
	v_mfma_f32_16x16x32_bf16 v[112:115], v[128:131], v[196:199], v[112:115]
	v_mfma_f32_16x16x32_bf16 v[120:123], v[132:135], v[196:199], v[120:123]
	v_mfma_f32_16x16x32_bf16 v[80:83], v[136:139], v[196:199], v[80:83]
	v_mfma_f32_16x16x32_bf16 v[88:91], v[140:143], v[196:199], v[88:91]
	ds_read_b128 v[196:199], v246 offset:4096
	s_waitcnt lgkmcnt(3)
	v_mfma_f32_16x16x32_bf16 v[116:119], v[128:131], v[200:203], v[116:119]
	v_mfma_f32_16x16x32_bf16 v[124:127], v[132:135], v[200:203], v[124:127]
	v_mfma_f32_16x16x32_bf16 v[84:87], v[136:139], v[200:203], v[84:87]
	v_mfma_f32_16x16x32_bf16 v[92:95], v[140:143], v[200:203], v[92:95]
	ds_read_b128 v[200:203], v246 offset:5120
	s_waitcnt lgkmcnt(3)
	v_mfma_f32_16x16x32_bf16 v[96:99], v[128:131], v[204:207], v[96:99]
	v_mfma_f32_16x16x32_bf16 v[104:107], v[132:135], v[204:207], v[104:107]
	v_mfma_f32_16x16x32_bf16 v[64:67], v[136:139], v[204:207], v[64:67]
	v_mfma_f32_16x16x32_bf16 v[72:75], v[140:143], v[204:207], v[72:75]
	ds_read_b128 v[204:207], v246 offset:6144
	s_waitcnt lgkmcnt(3)
	v_mfma_f32_16x16x32_bf16 v[100:103], v[128:131], v[242:245], v[100:103]
	v_mfma_f32_16x16x32_bf16 v[108:111], v[132:135], v[242:245], v[108:111]
	v_mfma_f32_16x16x32_bf16 v[68:71], v[136:139], v[242:245], v[68:71]
	v_mfma_f32_16x16x32_bf16 v[76:79], v[140:143], v[242:245], v[76:79]
	ds_read_b128 v[242:245], v246 offset:7168
	s_waitcnt vmcnt(6)
	ds_write_b128 v241, v[168:171] offset:8192
	ds_write_b128 v241, v[172:175] offset:12288
	s_waitcnt lgkmcnt(5)
	v_mfma_f32_16x16x32_bf16 v[48:51], v[128:131], v[196:199], v[48:51]
	v_mfma_f32_16x16x32_bf16 v[56:59], v[132:135], v[196:199], v[56:59]
	v_mfma_f32_16x16x32_bf16 v[16:19], v[136:139], v[196:199], v[16:19]
	v_mfma_f32_16x16x32_bf16 v[24:27], v[140:143], v[196:199], v[24:27]
	s_waitcnt lgkmcnt(4)
	v_mfma_f32_16x16x32_bf16 v[52:55], v[128:131], v[200:203], v[52:55]
	v_mfma_f32_16x16x32_bf16 v[60:63], v[132:135], v[200:203], v[60:63]
	v_mfma_f32_16x16x32_bf16 v[20:23], v[136:139], v[200:203], v[20:23]
	v_mfma_f32_16x16x32_bf16 v[28:31], v[140:143], v[200:203], v[28:31]
	s_waitcnt lgkmcnt(3)
	v_mfma_f32_16x16x32_bf16 v[32:35], v[128:131], v[204:207], v[32:35]
	v_mfma_f32_16x16x32_bf16 v[40:43], v[132:135], v[204:207], v[40:43]
	v_mfma_f32_16x16x32_bf16 v[0:3], v[136:139], v[204:207], v[0:3]
	v_mfma_f32_16x16x32_bf16 v[8:11], v[140:143], v[204:207], v[8:11]
	s_waitcnt lgkmcnt(2)
	v_mfma_f32_16x16x32_bf16 v[36:39], v[128:131], v[242:245], v[36:39]
	v_mfma_f32_16x16x32_bf16 v[44:47], v[132:135], v[242:245], v[44:47]
	v_mfma_f32_16x16x32_bf16 v[4:7], v[136:139], v[242:245], v[4:7]
	v_mfma_f32_16x16x32_bf16 v[12:15], v[140:143], v[242:245], v[12:15]
	global_load_dwordx4 v[128:131], v[248:249], off
	global_load_dwordx4 v[132:135], v[248:249], off offset:256
	global_load_dwordx4 v[136:139], v[250:251], off
	global_load_dwordx4 v[140:143], v[250:251], off offset:256
	s_waitcnt lgkmcnt(0)
	s_barrier
	s_add_i32 s8, s1, 3
	s_min_u32 s9, s8, 31
	s_lshl_b32 s96, s9, 13
	v_lshl_add_u64 v[174:175], v[188:189], 0, s[96:97]
	global_load_dwordx4 v[168:171], v[174:175], off offset:-2048
	global_load_dwordx4 v[172:175], v[174:175], off offset:2048
	ds_read_b128 v[196:199], v246 offset:8192
	ds_read_b128 v[200:203], v246 offset:9216
	ds_read_b128 v[204:207], v246 offset:10240
	ds_read_b128 v[242:245], v246 offset:11264
	s_lshl_b32 s96, s9, 11
	v_lshl_add_u64 v[248:249], v[184:185], 0, s[96:97]
	v_lshl_add_u64 v[250:251], v[186:187], 0, s[96:97]
	s_waitcnt vmcnt(8) lgkmcnt(3)
	v_mfma_f32_16x16x32_bf16 v[112:115], v[144:147], v[196:199], v[112:115]
	v_mfma_f32_16x16x32_bf16 v[120:123], v[148:151], v[196:199], v[120:123]
	v_mfma_f32_16x16x32_bf16 v[80:83], v[152:155], v[196:199], v[80:83]
	v_mfma_f32_16x16x32_bf16 v[88:91], v[156:159], v[196:199], v[88:91]
	ds_read_b128 v[196:199], v246 offset:12288
	s_waitcnt lgkmcnt(3)
	v_mfma_f32_16x16x32_bf16 v[116:119], v[144:147], v[200:203], v[116:119]
	v_mfma_f32_16x16x32_bf16 v[124:127], v[148:151], v[200:203], v[124:127]
	v_mfma_f32_16x16x32_bf16 v[84:87], v[152:155], v[200:203], v[84:87]
	v_mfma_f32_16x16x32_bf16 v[92:95], v[156:159], v[200:203], v[92:95]
	ds_read_b128 v[200:203], v246 offset:13312
	s_waitcnt lgkmcnt(3)
	v_mfma_f32_16x16x32_bf16 v[96:99], v[144:147], v[204:207], v[96:99]
	v_mfma_f32_16x16x32_bf16 v[104:107], v[148:151], v[204:207], v[104:107]
	v_mfma_f32_16x16x32_bf16 v[64:67], v[152:155], v[204:207], v[64:67]
	v_mfma_f32_16x16x32_bf16 v[72:75], v[156:159], v[204:207], v[72:75]
	ds_read_b128 v[204:207], v246 offset:14336
	s_waitcnt lgkmcnt(3)
	v_mfma_f32_16x16x32_bf16 v[100:103], v[144:147], v[242:245], v[100:103]
	v_mfma_f32_16x16x32_bf16 v[108:111], v[148:151], v[242:245], v[108:111]
	v_mfma_f32_16x16x32_bf16 v[68:71], v[152:155], v[242:245], v[68:71]
	v_mfma_f32_16x16x32_bf16 v[76:79], v[156:159], v[242:245], v[76:79]
	ds_read_b128 v[242:245], v246 offset:15360
	s_waitcnt vmcnt(6)
	ds_write_b128 v241, v[160:163] offset:0
	ds_write_b128 v241, v[164:167] offset:4096
	s_waitcnt lgkmcnt(5)
	v_mfma_f32_16x16x32_bf16 v[48:51], v[144:147], v[196:199], v[48:51]
	v_mfma_f32_16x16x32_bf16 v[56:59], v[148:151], v[196:199], v[56:59]
	v_mfma_f32_16x16x32_bf16 v[16:19], v[152:155], v[196:199], v[16:19]
	v_mfma_f32_16x16x32_bf16 v[24:27], v[156:159], v[196:199], v[24:27]
	s_waitcnt lgkmcnt(4)
	v_mfma_f32_16x16x32_bf16 v[52:55], v[144:147], v[200:203], v[52:55]
	v_mfma_f32_16x16x32_bf16 v[60:63], v[148:151], v[200:203], v[60:63]
	v_mfma_f32_16x16x32_bf16 v[20:23], v[152:155], v[200:203], v[20:23]
	v_mfma_f32_16x16x32_bf16 v[28:31], v[156:159], v[200:203], v[28:31]
	s_waitcnt lgkmcnt(3)
	v_mfma_f32_16x16x32_bf16 v[32:35], v[144:147], v[204:207], v[32:35]
	v_mfma_f32_16x16x32_bf16 v[40:43], v[148:151], v[204:207], v[40:43]
	v_mfma_f32_16x16x32_bf16 v[0:3], v[152:155], v[204:207], v[0:3]
	v_mfma_f32_16x16x32_bf16 v[8:11], v[156:159], v[204:207], v[8:11]
	s_waitcnt lgkmcnt(2)
	v_mfma_f32_16x16x32_bf16 v[36:39], v[144:147], v[242:245], v[36:39]
	v_mfma_f32_16x16x32_bf16 v[44:47], v[148:151], v[242:245], v[44:47]
	v_mfma_f32_16x16x32_bf16 v[4:7], v[152:155], v[242:245], v[4:7]
	v_mfma_f32_16x16x32_bf16 v[12:15], v[156:159], v[242:245], v[12:15]
	global_load_dwordx4 v[144:147], v[248:249], off
	global_load_dwordx4 v[148:151], v[248:249], off offset:256
	global_load_dwordx4 v[152:155], v[250:251], off
	global_load_dwordx4 v[156:159], v[250:251], off offset:256
	s_add_i32 s1, s1, 2
	s_cmp_lt_u32 s1, 32
	s_waitcnt lgkmcnt(0)
	s_barrier
	s_cbranch_scc1 .Lg16_gu_k
	s_nop 7
	v_permlane16_swap_b32_e32 v112, v116
	v_permlane16_swap_b32_e32 v113, v117
	v_permlane16_swap_b32_e32 v114, v118
	v_permlane16_swap_b32_e32 v115, v119
	v_permlane16_swap_b32_e32 v120, v124
	v_permlane16_swap_b32_e32 v121, v125
	v_permlane16_swap_b32_e32 v122, v126
	v_permlane16_swap_b32_e32 v123, v127
	v_permlane16_swap_b32_e32 v96, v100
	v_permlane16_swap_b32_e32 v97, v101
	v_permlane16_swap_b32_e32 v98, v102
	v_permlane16_swap_b32_e32 v99, v103
	v_permlane16_swap_b32_e32 v104, v108
	v_permlane16_swap_b32_e32 v105, v109
	v_permlane16_swap_b32_e32 v106, v110
	v_permlane16_swap_b32_e32 v107, v111
	v_permlane16_swap_b32_e32 v48, v52
	v_permlane16_swap_b32_e32 v49, v53
	v_permlane16_swap_b32_e32 v50, v54
	v_permlane16_swap_b32_e32 v51, v55
	v_permlane16_swap_b32_e32 v56, v60
	v_permlane16_swap_b32_e32 v57, v61
	v_permlane16_swap_b32_e32 v58, v62
	v_permlane16_swap_b32_e32 v59, v63
	v_permlane16_swap_b32_e32 v32, v36
	v_permlane16_swap_b32_e32 v33, v37
	v_permlane16_swap_b32_e32 v34, v38
	v_permlane16_swap_b32_e32 v35, v39
	v_permlane16_swap_b32_e32 v40, v44
	v_permlane16_swap_b32_e32 v41, v45
	v_permlane16_swap_b32_e32 v42, v46
	v_permlane16_swap_b32_e32 v43, v47
	v_permlane16_swap_b32_e32 v80, v84
	v_permlane16_swap_b32_e32 v81, v85
	v_permlane16_swap_b32_e32 v82, v86
	v_permlane16_swap_b32_e32 v83, v87
	v_permlane16_swap_b32_e32 v88, v92
	v_permlane16_swap_b32_e32 v89, v93
	v_permlane16_swap_b32_e32 v90, v94
	v_permlane16_swap_b32_e32 v91, v95
	v_permlane16_swap_b32_e32 v64, v68
	v_permlane16_swap_b32_e32 v65, v69
	v_permlane16_swap_b32_e32 v66, v70
	v_permlane16_swap_b32_e32 v67, v71
	v_permlane16_swap_b32_e32 v72, v76
	v_permlane16_swap_b32_e32 v73, v77
	v_permlane16_swap_b32_e32 v74, v78
	v_permlane16_swap_b32_e32 v75, v79
	v_permlane16_swap_b32_e32 v16, v20
	v_permlane16_swap_b32_e32 v17, v21
	v_permlane16_swap_b32_e32 v18, v22
	v_permlane16_swap_b32_e32 v19, v23
	v_permlane16_swap_b32_e32 v24, v28
	v_permlane16_swap_b32_e32 v25, v29
	v_permlane16_swap_b32_e32 v26, v30
	v_permlane16_swap_b32_e32 v27, v31
	v_permlane16_swap_b32_e32 v0, v4
	v_permlane16_swap_b32_e32 v1, v5
	v_permlane16_swap_b32_e32 v2, v6
	v_permlane16_swap_b32_e32 v3, v7
	v_permlane16_swap_b32_e32 v8, v12
	v_permlane16_swap_b32_e32 v9, v13
	v_permlane16_swap_b32_e32 v10, v14
	v_permlane16_swap_b32_e32 v11, v15
	v_permlane32_swap_b32_e32 v112, v116
	v_permlane32_swap_b32_e32 v113, v117
	v_permlane32_swap_b32_e32 v114, v118
	v_permlane32_swap_b32_e32 v115, v119
	v_permlane32_swap_b32_e32 v120, v124
	v_permlane32_swap_b32_e32 v121, v125
	v_permlane32_swap_b32_e32 v122, v126
	v_permlane32_swap_b32_e32 v123, v127
	v_permlane32_swap_b32_e32 v96, v100
	v_permlane32_swap_b32_e32 v97, v101
	v_permlane32_swap_b32_e32 v98, v102
	v_permlane32_swap_b32_e32 v99, v103
	v_permlane32_swap_b32_e32 v104, v108
	v_permlane32_swap_b32_e32 v105, v109
	v_permlane32_swap_b32_e32 v106, v110
	v_permlane32_swap_b32_e32 v107, v111
	v_permlane32_swap_b32_e32 v48, v52
	v_permlane32_swap_b32_e32 v49, v53
	v_permlane32_swap_b32_e32 v50, v54
	v_permlane32_swap_b32_e32 v51, v55
	v_permlane32_swap_b32_e32 v56, v60
	v_permlane32_swap_b32_e32 v57, v61
	v_permlane32_swap_b32_e32 v58, v62
	v_permlane32_swap_b32_e32 v59, v63
	v_permlane32_swap_b32_e32 v32, v36
	v_permlane32_swap_b32_e32 v33, v37
	v_permlane32_swap_b32_e32 v34, v38
	v_permlane32_swap_b32_e32 v35, v39
	v_permlane32_swap_b32_e32 v40, v44
	v_permlane32_swap_b32_e32 v41, v45
	v_permlane32_swap_b32_e32 v42, v46
	v_permlane32_swap_b32_e32 v43, v47
	v_permlane32_swap_b32_e32 v80, v84
	v_permlane32_swap_b32_e32 v81, v85
	v_permlane32_swap_b32_e32 v82, v86
	v_permlane32_swap_b32_e32 v83, v87
	v_permlane32_swap_b32_e32 v88, v92
	v_permlane32_swap_b32_e32 v89, v93
	v_permlane32_swap_b32_e32 v90, v94
	v_permlane32_swap_b32_e32 v91, v95
	v_permlane32_swap_b32_e32 v64, v68
	v_permlane32_swap_b32_e32 v65, v69
	v_permlane32_swap_b32_e32 v66, v70
	v_permlane32_swap_b32_e32 v67, v71
	v_permlane32_swap_b32_e32 v72, v76
	v_permlane32_swap_b32_e32 v73, v77
	v_permlane32_swap_b32_e32 v74, v78
	v_permlane32_swap_b32_e32 v75, v79
	v_permlane32_swap_b32_e32 v16, v20
	v_permlane32_swap_b32_e32 v17, v21
	v_permlane32_swap_b32_e32 v18, v22
	v_permlane32_swap_b32_e32 v19, v23
	v_permlane32_swap_b32_e32 v24, v28
	v_permlane32_swap_b32_e32 v25, v29
	v_permlane32_swap_b32_e32 v26, v30
	v_permlane32_swap_b32_e32 v27, v31
	v_permlane32_swap_b32_e32 v0, v4
	v_permlane32_swap_b32_e32 v1, v5
	v_permlane32_swap_b32_e32 v2, v6
	v_permlane32_swap_b32_e32 v3, v7
	v_permlane32_swap_b32_e32 v8, v12
	v_permlane32_swap_b32_e32 v9, v13
	v_permlane32_swap_b32_e32 v10, v14
	v_permlane32_swap_b32_e32 v11, v15
	s_waitcnt vmcnt(0)
	s_waitcnt vmcnt(0)
	v_mul_f32_e32 v133, 0xbfb8aa3b, v112
	v_exp_f32_e32 v133, v133
	s_movk_i32 s1, 0x2400
	v_mul_lo_u32 v128, v238, s1
	v_lshl_or_b32 v131, s0, 6, v181
	v_add_f32_e32 v133, 1.0, v133
	v_lshl_or_b32 v132, v239, 1, v128
	v_and_b32_e32 v129, 0xffffffc0, v237
	v_lshl_or_b32 v128, v181, 1, v128
	v_rcp_f32_e32 v135, v133
	s_nop 0
	v_mul_f32_e32 v112, v112, v135
	v_mul_f32_e32 v96, v96, v112
	v_cvt_pk_bf16_f32 v112, v96, s0
	s_movk_i32 s0, 0x240
	v_mad_u32_u24 v96, v183, s0, v132
	ds_write_b16 v96, v112
	v_mul_f32_e32 v112, 0xbfb8aa3b, v113
	v_exp_f32_e32 v112, v112
	v_lshl_add_u32 v130, s7, 8, v129
	v_lshrrev_b32_e32 v129, 2, v240
	v_mad_u32_u24 v128, v129, s42, v128
	v_add_f32_e32 v112, 1.0, v112
	v_rcp_f32_e32 v133, v112
	s_nop 0
	v_mul_f32_e32 v112, v113, v133
	v_mul_f32_e32 v97, v97, v112
	v_cvt_pk_bf16_f32 v97, v97, s0
	ds_write_b16 v96, v97 offset:144
	v_mul_f32_e32 v97, 0xbfb8aa3b, v114
	v_exp_f32_e32 v97, v97
	s_nop 0
	v_add_f32_e32 v97, 1.0, v97
	v_rcp_f32_e32 v113, v97
	s_nop 0
	v_mul_f32_e32 v97, v114, v113
	v_mul_f32_e32 v97, v98, v97
	v_cvt_pk_bf16_f32 v97, v97, s0
	ds_write_b16 v96, v97 offset:288
	v_mul_f32_e32 v97, 0xbfb8aa3b, v115
	v_exp_f32_e32 v97, v97
	s_nop 0
	v_add_f32_e32 v97, 1.0, v97
	v_rcp_f32_e32 v112, v97
	s_nop 0
	v_mul_f32_e32 v97, v115, v112
	v_mul_f32_e32 v97, v99, v97
	v_cvt_pk_bf16_f32 v97, v97, s0
	ds_write_b16 v96, v97 offset:432
	v_mul_f32_e32 v97, 0xbfb8aa3b, v116
	v_exp_f32_e32 v97, v97
	s_nop 0
	v_add_f32_e32 v97, 1.0, v97
	v_rcp_f32_e32 v99, v97
	s_nop 0
	v_mul_f32_e32 v97, v116, v99
	v_mul_f32_e32 v97, v100, v97
	v_cvt_pk_bf16_f32 v97, v97, s0
	ds_write_b16 v96, v97 offset:1152
	v_mul_f32_e32 v97, 0xbfb8aa3b, v117
	v_exp_f32_e32 v97, v97
	s_nop 0
	v_add_f32_e32 v97, 1.0, v97
	v_rcp_f32_e32 v99, v97
	s_nop 0
	v_mul_f32_e32 v97, v117, v99
	v_mul_f32_e32 v97, v101, v97
	v_cvt_pk_bf16_f32 v97, v97, s0
	ds_write_b16 v96, v97 offset:1296
	v_mul_f32_e32 v97, 0xbfb8aa3b, v118
	v_exp_f32_e32 v97, v97
	s_nop 0
	v_add_f32_e32 v97, 1.0, v97
	v_rcp_f32_e32 v99, v97
	s_nop 0
	v_mul_f32_e32 v97, v118, v99
	v_mul_f32_e32 v97, v102, v97
	v_cvt_pk_bf16_f32 v97, v97, s0
	ds_write_b16 v96, v97 offset:1440
	v_mul_f32_e32 v97, 0xbfb8aa3b, v119
	v_exp_f32_e32 v97, v97
	s_nop 0
	v_add_f32_e32 v97, 1.0, v97
	v_rcp_f32_e32 v99, v97
	s_nop 0
	v_mul_f32_e32 v97, v119, v99
	v_mul_f32_e32 v97, v103, v97
	v_cvt_pk_bf16_f32 v97, v97, s0
	ds_write_b16 v96, v97 offset:1584
	v_mul_f32_e32 v97, 0xbfb8aa3b, v120
	v_exp_f32_e32 v97, v97
	s_nop 0
	v_add_f32_e32 v97, 1.0, v97
	v_rcp_f32_e32 v99, v97
	s_nop 0
	v_mul_f32_e32 v97, v120, v99
	v_mul_f32_e32 v97, v104, v97
	v_cvt_pk_bf16_f32 v97, v97, s0
	ds_write_b16 v96, v97 offset:2304
	v_mul_f32_e32 v97, 0xbfb8aa3b, v121
	v_exp_f32_e32 v97, v97
	s_nop 0
	v_add_f32_e32 v97, 1.0, v97
	v_rcp_f32_e32 v99, v97
	s_nop 0
	v_mul_f32_e32 v97, v121, v99
	v_mul_f32_e32 v97, v105, v97
	v_cvt_pk_bf16_f32 v97, v97, s0
	ds_write_b16 v96, v97 offset:2448
	v_mul_f32_e32 v97, 0xbfb8aa3b, v122
	v_exp_f32_e32 v97, v97
	s_nop 0
	v_add_f32_e32 v97, 1.0, v97
	v_rcp_f32_e32 v99, v97
	s_nop 0
	v_mul_f32_e32 v97, v122, v99
	v_mul_f32_e32 v97, v106, v97
	v_cvt_pk_bf16_f32 v97, v97, s0
	ds_write_b16 v96, v97 offset:2592
	v_mul_f32_e32 v97, 0xbfb8aa3b, v123
	v_exp_f32_e32 v97, v97
	s_nop 0
	v_add_f32_e32 v97, 1.0, v97
	v_rcp_f32_e32 v99, v97
	s_nop 0
	v_mul_f32_e32 v97, v123, v99
	v_mul_f32_e32 v97, v107, v97
	v_cvt_pk_bf16_f32 v97, v97, s0
	ds_write_b16 v96, v97 offset:2736
	v_mul_f32_e32 v97, 0xbfb8aa3b, v124
	v_exp_f32_e32 v97, v97
	s_nop 0
	v_add_f32_e32 v97, 1.0, v97
	v_rcp_f32_e32 v99, v97
	s_nop 0
	v_mul_f32_e32 v97, v124, v99
	v_mul_f32_e32 v97, v108, v97
	v_cvt_pk_bf16_f32 v97, v97, s0
	ds_write_b16 v96, v97 offset:3456
	v_mul_f32_e32 v97, 0xbfb8aa3b, v125
	v_exp_f32_e32 v97, v97
	s_nop 0
	v_add_f32_e32 v97, 1.0, v97
	v_rcp_f32_e32 v99, v97
	s_nop 0
	v_mul_f32_e32 v97, v125, v99
	v_mul_f32_e32 v97, v109, v97
	v_cvt_pk_bf16_f32 v97, v97, s0
	ds_write_b16 v96, v97 offset:3600
	v_mul_f32_e32 v97, 0xbfb8aa3b, v126
	v_exp_f32_e32 v97, v97
	s_nop 0
	v_add_f32_e32 v97, 1.0, v97
	v_rcp_f32_e32 v99, v97
	s_nop 0
	v_mul_f32_e32 v97, v126, v99
	v_mul_f32_e32 v97, v110, v97
	v_cvt_pk_bf16_f32 v97, v97, s0
	ds_write_b16 v96, v97 offset:3744
	v_mul_f32_e32 v97, 0xbfb8aa3b, v127
	v_exp_f32_e32 v97, v97
	s_nop 0
	v_add_f32_e32 v97, 1.0, v97
	v_rcp_f32_e32 v99, v97
	s_nop 0
	v_mul_f32_e32 v97, v127, v99
	v_mul_f32_e32 v97, v111, v97
	v_cvt_pk_bf16_f32 v97, v97, s0
	ds_write_b16 v96, v97 offset:3888
	v_mul_f32_e32 v97, 0xbfb8aa3b, v80
	v_exp_f32_e32 v97, v97
	s_nop 0
	v_add_f32_e32 v97, 1.0, v97
	v_rcp_f32_e32 v99, v97
	s_nop 0
	v_mul_f32_e32 v80, v80, v99
	v_mul_f32_e32 v64, v64, v80
	v_cvt_pk_bf16_f32 v64, v64, s0
	ds_write_b16 v96, v64 offset:4608
	v_mul_f32_e32 v64, 0xbfb8aa3b, v81
	v_exp_f32_e32 v64, v64
	s_nop 0
	v_add_f32_e32 v64, 1.0, v64
	v_rcp_f32_e32 v97, v64
	s_nop 0
	v_mul_f32_e32 v64, v81, v97
	v_mul_f32_e32 v64, v65, v64
	v_cvt_pk_bf16_f32 v64, v64, s0
	ds_write_b16 v96, v64 offset:4752
	v_mul_f32_e32 v64, 0xbfb8aa3b, v82
	v_exp_f32_e32 v64, v64
	s_nop 0
	v_add_f32_e32 v64, 1.0, v64
	v_rcp_f32_e32 v80, v64
	s_nop 0
	v_mul_f32_e32 v64, v82, v80
	v_mul_f32_e32 v64, v66, v64
	v_cvt_pk_bf16_f32 v64, v64, s0
	ds_write_b16 v96, v64 offset:4896
	v_mul_f32_e32 v64, 0xbfb8aa3b, v83
	v_exp_f32_e32 v64, v64
	s_nop 0
	v_add_f32_e32 v64, 1.0, v64
	v_rcp_f32_e32 v66, v64
	s_nop 0
	v_mul_f32_e32 v64, v83, v66
	v_mul_f32_e32 v64, v67, v64
	v_cvt_pk_bf16_f32 v64, v64, s0
	ds_write_b16 v96, v64 offset:5040
	v_mul_f32_e32 v64, 0xbfb8aa3b, v84
	v_exp_f32_e32 v64, v64
	s_nop 0
	v_add_f32_e32 v64, 1.0, v64
	v_rcp_f32_e32 v66, v64
	s_nop 0
	v_mul_f32_e32 v64, v84, v66
	v_mul_f32_e32 v64, v68, v64
	v_cvt_pk_bf16_f32 v64, v64, s0
	ds_write_b16 v96, v64 offset:5760
	v_mul_f32_e32 v64, 0xbfb8aa3b, v85
	v_exp_f32_e32 v64, v64
	s_nop 0
	v_add_f32_e32 v64, 1.0, v64
	v_rcp_f32_e32 v66, v64
	s_nop 0
	v_mul_f32_e32 v64, v85, v66
	v_mul_f32_e32 v64, v69, v64
	v_cvt_pk_bf16_f32 v64, v64, s0
	ds_write_b16 v96, v64 offset:5904
	v_mul_f32_e32 v64, 0xbfb8aa3b, v86
	v_exp_f32_e32 v64, v64
	s_nop 0
	v_add_f32_e32 v64, 1.0, v64
	v_rcp_f32_e32 v66, v64
	s_nop 0
	v_mul_f32_e32 v64, v86, v66
	v_mul_f32_e32 v64, v70, v64
	v_cvt_pk_bf16_f32 v64, v64, s0
	ds_write_b16 v96, v64 offset:6048
	v_mul_f32_e32 v64, 0xbfb8aa3b, v87
	v_exp_f32_e32 v64, v64
	s_nop 0
	v_add_f32_e32 v64, 1.0, v64
	v_rcp_f32_e32 v66, v64
	s_nop 0
	v_mul_f32_e32 v64, v87, v66
	v_mul_f32_e32 v64, v71, v64
	v_cvt_pk_bf16_f32 v64, v64, s0
	ds_write_b16 v96, v64 offset:6192
	v_mul_f32_e32 v64, 0xbfb8aa3b, v88
	v_exp_f32_e32 v64, v64
	v_ashrrev_i32_e32 v71, 5, v130
	v_or_b32_e32 v70, 1, v71
	v_add_f32_e32 v64, 1.0, v64
	v_rcp_f32_e32 v66, v64
	s_nop 0
	v_mul_f32_e32 v64, v88, v66
	v_mul_f32_e32 v64, v72, v64
	v_cvt_pk_bf16_f32 v64, v64, s0
	ds_write_b16 v96, v64 offset:6912
	v_mul_f32_e32 v64, 0xbfb8aa3b, v89
	v_exp_f32_e32 v64, v64
	s_nop 0
	v_add_f32_e32 v64, 1.0, v64
	v_rcp_f32_e32 v66, v64
	s_nop 0
	v_mul_f32_e32 v64, v89, v66
	v_mul_f32_e32 v64, v73, v64
	v_cvt_pk_bf16_f32 v64, v64, s0
	ds_write_b16 v96, v64 offset:7056
	v_mul_f32_e32 v64, 0xbfb8aa3b, v90
	v_exp_f32_e32 v64, v64
	s_nop 0
	v_add_f32_e32 v64, 1.0, v64
	v_rcp_f32_e32 v66, v64
	s_nop 0
	v_mul_f32_e32 v64, v90, v66
	v_mul_f32_e32 v64, v74, v64
	v_cvt_pk_bf16_f32 v64, v64, s0
	ds_write_b16 v96, v64 offset:7200
	v_mul_f32_e32 v64, 0xbfb8aa3b, v91
	v_exp_f32_e32 v64, v64
	s_nop 0
	v_add_f32_e32 v64, 1.0, v64
	v_rcp_f32_e32 v66, v64
	s_nop 0
	v_mul_f32_e32 v64, v91, v66
	v_mul_f32_e32 v64, v75, v64
	v_cvt_pk_bf16_f32 v64, v64, s0
	ds_write_b16 v96, v64 offset:7344
	v_mul_f32_e32 v64, 0xbfb8aa3b, v92
	v_exp_f32_e32 v64, v64
	s_nop 0
	v_add_f32_e32 v64, 1.0, v64
	v_rcp_f32_e32 v66, v64
	s_nop 0
	v_mul_f32_e32 v64, v92, v66
	v_mul_f32_e32 v64, v76, v64
	v_cvt_pk_bf16_f32 v64, v64, s0
	ds_write_b16 v96, v64 offset:8064
	v_mul_f32_e32 v64, 0xbfb8aa3b, v93
	v_exp_f32_e32 v64, v64
	s_nop 0
	v_add_f32_e32 v64, 1.0, v64
	v_rcp_f32_e32 v66, v64
	s_nop 0
	v_mul_f32_e32 v64, v93, v66
	v_mul_f32_e32 v64, v77, v64
	v_cvt_pk_bf16_f32 v64, v64, s0
	ds_write_b16 v96, v64 offset:8208
	v_mul_f32_e32 v64, 0xbfb8aa3b, v94
	v_exp_f32_e32 v64, v64
	s_nop 0
	v_add_f32_e32 v64, 1.0, v64
	v_rcp_f32_e32 v66, v64
	s_nop 0
	v_mul_f32_e32 v64, v94, v66
	v_mul_f32_e32 v64, v78, v64
	v_cvt_pk_bf16_f32 v64, v64, s0
	ds_write_b16 v96, v64 offset:8352
	v_mul_f32_e32 v64, 0xbfb8aa3b, v95
	v_exp_f32_e32 v64, v64
	s_nop 0
	v_add_f32_e32 v64, 1.0, v64
	v_rcp_f32_e32 v66, v64
	s_nop 0
	v_mul_f32_e32 v64, v95, v66
	v_mul_f32_e32 v64, v79, v64
	v_cvt_pk_bf16_f32 v64, v64, s0
	ds_write_b16 v96, v64 offset:8496
	v_ashrrev_i32_e32 v68, 4, v131
	s_waitcnt lgkmcnt(0)
	v_ashrrev_i32_e32 v69, 31, v68
	ds_read_b128 v[72:75], v128
	v_mad_i64_i32 v[64:65], s[0:1], v71, s23, v[68:69]
	v_lshlrev_b64 v[64:65], 10, v[64:65]
	v_lshlrev_b32_e32 v66, 6, v181
	v_lshl_add_u64 v[64:65], s[66:67], 0, v[64:65]
	v_and_b32_e32 v176, 0x200, v66
	v_lshl_add_u64 v[76:77], v[64:65], 0, v[176:177]
	v_lshlrev_b32_e32 v66, 4, v129
	v_mov_b32_e32 v67, v177
	v_lshl_add_u64 v[64:65], v[76:77], 0, v[66:67]
	s_waitcnt lgkmcnt(0)
	global_store_dwordx4 v[64:65], v[72:75], off
	ds_read_b128 v[72:75], v128 offset:2304
	v_or_b32_e32 v64, 0x100, v66
	v_mov_b32_e32 v65, v177
	v_lshl_add_u64 v[76:77], v[76:77], 0, v[64:65]
	s_waitcnt lgkmcnt(0)
	global_store_dwordx4 v[76:77], v[72:75], off
	ds_read_b128 v[72:75], v128 offset:4608
	v_mad_i64_i32 v[76:77], s[0:1], v70, s23, v[68:69]
	v_lshlrev_b64 v[76:77], 10, v[76:77]
	v_lshl_add_u64 v[76:77], s[66:67], 0, v[76:77]
	v_lshl_add_u64 v[76:77], v[76:77], 0, v[176:177]
	v_lshl_add_u64 v[78:79], v[76:77], 0, v[66:67]
	v_mul_f32_e32 v69, 0xbfb8aa3b, v48
	s_waitcnt lgkmcnt(0)
	global_store_dwordx4 v[78:79], v[72:75], off
	ds_read_b128 v[72:75], v128 offset:6912
	v_exp_f32_e32 v69, v69
	v_lshl_add_u64 v[76:77], v[76:77], 0, v[64:65]
	v_add_f32_e32 v69, 1.0, v69
	s_waitcnt lgkmcnt(0)
	global_store_dwordx4 v[76:77], v[72:75], off
	s_waitcnt lgkmcnt(0)
	s_nop 1
	v_rcp_f32_e32 v73, v69
	s_nop 0
	v_mul_f32_e32 v48, v48, v73
	v_mul_f32_e32 v32, v32, v48
	v_cvt_pk_bf16_f32 v32, v32, s0
	ds_write_b16 v96, v32
	v_mul_f32_e32 v32, 0xbfb8aa3b, v49
	v_exp_f32_e32 v32, v32
	s_nop 0
	v_add_f32_e32 v32, 1.0, v32
	v_rcp_f32_e32 v69, v32
	s_nop 0
	v_mul_f32_e32 v32, v49, v69
	v_mul_f32_e32 v32, v33, v32
	v_cvt_pk_bf16_f32 v32, v32, s0
	ds_write_b16 v96, v32 offset:144
	v_mul_f32_e32 v32, 0xbfb8aa3b, v50
	v_exp_f32_e32 v32, v32
	s_nop 0
	v_add_f32_e32 v32, 1.0, v32
	v_rcp_f32_e32 v48, v32
	s_nop 0
	v_mul_f32_e32 v32, v50, v48
	v_mul_f32_e32 v32, v34, v32
	v_cvt_pk_bf16_f32 v32, v32, s0
	ds_write_b16 v96, v32 offset:288
	v_mul_f32_e32 v32, 0xbfb8aa3b, v51
	v_exp_f32_e32 v32, v32
	s_nop 0
	v_add_f32_e32 v32, 1.0, v32
	v_rcp_f32_e32 v34, v32
	s_nop 0
	v_mul_f32_e32 v32, v51, v34
	v_mul_f32_e32 v32, v35, v32
	v_cvt_pk_bf16_f32 v32, v32, s0
	ds_write_b16 v96, v32 offset:432
	v_mul_f32_e32 v32, 0xbfb8aa3b, v52
	v_exp_f32_e32 v32, v32
	s_nop 0
	v_add_f32_e32 v32, 1.0, v32
	v_rcp_f32_e32 v34, v32
	s_nop 0
	v_mul_f32_e32 v32, v52, v34
	v_mul_f32_e32 v32, v36, v32
	v_cvt_pk_bf16_f32 v32, v32, s0
	ds_write_b16 v96, v32 offset:1152
	v_mul_f32_e32 v32, 0xbfb8aa3b, v53
	v_exp_f32_e32 v32, v32
	s_nop 0
	v_add_f32_e32 v32, 1.0, v32
	v_rcp_f32_e32 v34, v32
	s_nop 0
	v_mul_f32_e32 v32, v53, v34
	v_mul_f32_e32 v32, v37, v32
	v_cvt_pk_bf16_f32 v32, v32, s0
	ds_write_b16 v96, v32 offset:1296
	v_mul_f32_e32 v32, 0xbfb8aa3b, v54
	v_exp_f32_e32 v32, v32
	s_nop 0
	v_add_f32_e32 v32, 1.0, v32
	v_rcp_f32_e32 v34, v32
	s_nop 0
	v_mul_f32_e32 v32, v54, v34
	v_mul_f32_e32 v32, v38, v32
	v_cvt_pk_bf16_f32 v32, v32, s0
	ds_write_b16 v96, v32 offset:1440
	v_mul_f32_e32 v32, 0xbfb8aa3b, v55
	v_exp_f32_e32 v32, v32
	s_nop 0
	v_add_f32_e32 v32, 1.0, v32
	v_rcp_f32_e32 v34, v32
	s_nop 0
	v_mul_f32_e32 v32, v55, v34
	v_mul_f32_e32 v32, v39, v32
	v_cvt_pk_bf16_f32 v32, v32, s0
	ds_write_b16 v96, v32 offset:1584
	v_mul_f32_e32 v32, 0xbfb8aa3b, v56
	v_exp_f32_e32 v32, v32
	s_nop 0
	v_add_f32_e32 v32, 1.0, v32
	v_rcp_f32_e32 v34, v32
	s_nop 0
	v_mul_f32_e32 v32, v56, v34
	v_mul_f32_e32 v32, v40, v32
	v_cvt_pk_bf16_f32 v32, v32, s0
	ds_write_b16 v96, v32 offset:2304
	v_mul_f32_e32 v32, 0xbfb8aa3b, v57
	v_exp_f32_e32 v32, v32
	s_nop 0
	v_add_f32_e32 v32, 1.0, v32
	v_rcp_f32_e32 v34, v32
	s_nop 0
	v_mul_f32_e32 v32, v57, v34
	v_mul_f32_e32 v32, v41, v32
	v_cvt_pk_bf16_f32 v32, v32, s0
	ds_write_b16 v96, v32 offset:2448
	v_mul_f32_e32 v32, 0xbfb8aa3b, v58
	v_exp_f32_e32 v32, v32
	s_nop 0
	v_add_f32_e32 v32, 1.0, v32
	v_rcp_f32_e32 v34, v32
	s_nop 0
	v_mul_f32_e32 v32, v58, v34
	v_mul_f32_e32 v32, v42, v32
	v_cvt_pk_bf16_f32 v32, v32, s0
	ds_write_b16 v96, v32 offset:2592
	v_mul_f32_e32 v32, 0xbfb8aa3b, v59
	v_exp_f32_e32 v32, v32
	s_nop 0
	v_add_f32_e32 v32, 1.0, v32
	v_rcp_f32_e32 v34, v32
	s_nop 0
	v_mul_f32_e32 v32, v59, v34
	v_mul_f32_e32 v32, v43, v32
	v_cvt_pk_bf16_f32 v32, v32, s0
	ds_write_b16 v96, v32 offset:2736
	v_mul_f32_e32 v32, 0xbfb8aa3b, v60
	v_exp_f32_e32 v32, v32
	s_nop 0
	v_add_f32_e32 v32, 1.0, v32
	v_rcp_f32_e32 v34, v32
	s_nop 0
	v_mul_f32_e32 v32, v60, v34
	v_mul_f32_e32 v32, v44, v32
	v_cvt_pk_bf16_f32 v32, v32, s0
	ds_write_b16 v96, v32 offset:3456
	v_mul_f32_e32 v32, 0xbfb8aa3b, v61
	v_exp_f32_e32 v32, v32
	s_nop 0
	v_add_f32_e32 v32, 1.0, v32
	v_rcp_f32_e32 v34, v32
	s_nop 0
	v_mul_f32_e32 v32, v61, v34
	v_mul_f32_e32 v32, v45, v32
	v_cvt_pk_bf16_f32 v32, v32, s0
	ds_write_b16 v96, v32 offset:3600
	v_mul_f32_e32 v32, 0xbfb8aa3b, v62
	v_exp_f32_e32 v32, v32
	s_nop 0
	v_add_f32_e32 v32, 1.0, v32
	v_rcp_f32_e32 v34, v32
	s_nop 0
	v_mul_f32_e32 v32, v62, v34
	v_mul_f32_e32 v32, v46, v32
	v_cvt_pk_bf16_f32 v32, v32, s0
	ds_write_b16 v96, v32 offset:3744
	v_mul_f32_e32 v32, 0xbfb8aa3b, v63
	v_exp_f32_e32 v32, v32
	s_nop 0
	v_add_f32_e32 v32, 1.0, v32
	v_rcp_f32_e32 v34, v32
	s_nop 0
	v_mul_f32_e32 v32, v63, v34
	v_mul_f32_e32 v32, v47, v32
	v_cvt_pk_bf16_f32 v32, v32, s0
	ds_write_b16 v96, v32 offset:3888
	v_mul_f32_e32 v32, 0xbfb8aa3b, v16
	v_exp_f32_e32 v32, v32
	s_nop 0
	v_add_f32_e32 v32, 1.0, v32
	v_rcp_f32_e32 v34, v32
	s_nop 0
	v_mul_f32_e32 v16, v16, v34
	v_mul_f32_e32 v0, v0, v16
	v_cvt_pk_bf16_f32 v0, v0, s0
	ds_write_b16 v96, v0 offset:4608
	v_mul_f32_e32 v0, 0xbfb8aa3b, v17
	v_exp_f32_e32 v0, v0
	s_nop 0
	v_add_f32_e32 v0, 1.0, v0
	v_rcp_f32_e32 v32, v0
	s_nop 0
	v_mul_f32_e32 v0, v17, v32
	v_mul_f32_e32 v0, v1, v0
	v_cvt_pk_bf16_f32 v0, v0, s0
	ds_write_b16 v96, v0 offset:4752
	v_mul_f32_e32 v0, 0xbfb8aa3b, v18
	v_exp_f32_e32 v0, v0
	s_nop 0
	v_add_f32_e32 v0, 1.0, v0
	v_rcp_f32_e32 v16, v0
	s_nop 0
	v_mul_f32_e32 v0, v18, v16
	v_mul_f32_e32 v0, v2, v0
	v_cvt_pk_bf16_f32 v0, v0, s0
	ds_write_b16 v96, v0 offset:4896
	v_mul_f32_e32 v0, 0xbfb8aa3b, v19
	v_exp_f32_e32 v0, v0
	s_nop 0
	v_add_f32_e32 v0, 1.0, v0
	v_rcp_f32_e32 v2, v0
	s_nop 0
	v_mul_f32_e32 v0, v19, v2
	v_mul_f32_e32 v0, v3, v0
	v_cvt_pk_bf16_f32 v0, v0, s0
	ds_write_b16 v96, v0 offset:5040
	v_mul_f32_e32 v0, 0xbfb8aa3b, v20
	v_exp_f32_e32 v0, v0
	s_nop 0
	v_add_f32_e32 v0, 1.0, v0
	v_rcp_f32_e32 v2, v0
	s_nop 0
	v_mul_f32_e32 v0, v20, v2
	v_mul_f32_e32 v0, v4, v0
	v_cvt_pk_bf16_f32 v0, v0, s0
	ds_write_b16 v96, v0 offset:5760
	v_mul_f32_e32 v0, 0xbfb8aa3b, v21
	v_exp_f32_e32 v0, v0
	s_nop 0
	v_add_f32_e32 v0, 1.0, v0
	v_rcp_f32_e32 v2, v0
	s_nop 0
	v_mul_f32_e32 v0, v21, v2
	v_mul_f32_e32 v0, v5, v0
	v_cvt_pk_bf16_f32 v0, v0, s0
	ds_write_b16 v96, v0 offset:5904
	v_mul_f32_e32 v0, 0xbfb8aa3b, v22
	v_exp_f32_e32 v0, v0
	s_nop 0
	v_add_f32_e32 v0, 1.0, v0
	v_rcp_f32_e32 v2, v0
	s_nop 0
	v_mul_f32_e32 v0, v22, v2
	v_mul_f32_e32 v0, v6, v0
	v_cvt_pk_bf16_f32 v0, v0, s0
	ds_write_b16 v96, v0 offset:6048
	v_mul_f32_e32 v0, 0xbfb8aa3b, v23
	v_exp_f32_e32 v0, v0
	s_nop 0
	v_add_f32_e32 v0, 1.0, v0
	v_rcp_f32_e32 v2, v0
	s_nop 0
	v_mul_f32_e32 v0, v23, v2
	v_mul_f32_e32 v0, v7, v0
	v_cvt_pk_bf16_f32 v0, v0, s0
	ds_write_b16 v96, v0 offset:6192
	v_mul_f32_e32 v0, 0xbfb8aa3b, v24
	v_exp_f32_e32 v0, v0
	s_nop 0
	v_add_f32_e32 v0, 1.0, v0
	v_rcp_f32_e32 v2, v0
	s_nop 0
	v_mul_f32_e32 v0, v24, v2
	v_mul_f32_e32 v0, v8, v0
	v_cvt_pk_bf16_f32 v0, v0, s0
	ds_write_b16 v96, v0 offset:6912
	v_mul_f32_e32 v0, 0xbfb8aa3b, v25
	v_exp_f32_e32 v0, v0
	s_nop 0
	v_add_f32_e32 v0, 1.0, v0
	v_rcp_f32_e32 v2, v0
	s_nop 0
	v_mul_f32_e32 v0, v25, v2
	v_mul_f32_e32 v0, v9, v0
	v_cvt_pk_bf16_f32 v0, v0, s0
	ds_write_b16 v96, v0 offset:7056
	v_mul_f32_e32 v0, 0xbfb8aa3b, v26
	v_exp_f32_e32 v0, v0
	s_nop 0
	v_add_f32_e32 v0, 1.0, v0
	v_rcp_f32_e32 v2, v0
	s_nop 0
	v_mul_f32_e32 v0, v26, v2
	v_mul_f32_e32 v0, v10, v0
	v_cvt_pk_bf16_f32 v0, v0, s0
	ds_write_b16 v96, v0 offset:7200
	v_mul_f32_e32 v0, 0xbfb8aa3b, v27
	v_exp_f32_e32 v0, v0
	s_nop 0
	v_add_f32_e32 v0, 1.0, v0
	v_rcp_f32_e32 v2, v0
	s_nop 0
	v_mul_f32_e32 v0, v27, v2
	v_mul_f32_e32 v0, v11, v0
	v_cvt_pk_bf16_f32 v0, v0, s0
	ds_write_b16 v96, v0 offset:7344
	v_mul_f32_e32 v0, 0xbfb8aa3b, v28
	v_exp_f32_e32 v0, v0
	s_nop 0
	v_add_f32_e32 v0, 1.0, v0
	v_rcp_f32_e32 v2, v0
	s_nop 0
	v_mul_f32_e32 v0, v28, v2
	v_mul_f32_e32 v0, v12, v0
	v_cvt_pk_bf16_f32 v0, v0, s0
	ds_write_b16 v96, v0 offset:8064
	v_mul_f32_e32 v0, 0xbfb8aa3b, v29
	v_exp_f32_e32 v0, v0
	s_nop 0
	v_add_f32_e32 v0, 1.0, v0
	v_rcp_f32_e32 v2, v0
	s_nop 0
	v_mul_f32_e32 v0, v29, v2
	v_mul_f32_e32 v0, v13, v0
	v_cvt_pk_bf16_f32 v0, v0, s0
	ds_write_b16 v96, v0 offset:8208
	v_mul_f32_e32 v0, 0xbfb8aa3b, v30
	v_exp_f32_e32 v0, v0
	s_nop 0
	v_add_f32_e32 v0, 1.0, v0
	v_rcp_f32_e32 v2, v0
	s_nop 0
	v_mul_f32_e32 v0, v30, v2
	v_mul_f32_e32 v0, v14, v0
	v_cvt_pk_bf16_f32 v0, v0, s0
	ds_write_b16 v96, v0 offset:8352
	v_mul_f32_e32 v0, 0xbfb8aa3b, v31
	v_exp_f32_e32 v0, v0
	s_nop 0
	v_add_f32_e32 v0, 1.0, v0
	v_rcp_f32_e32 v2, v0
	s_nop 0
	v_mul_f32_e32 v0, v31, v2
	v_mul_f32_e32 v0, v15, v0
	v_cvt_pk_bf16_f32 v0, v0, s0
	ds_write_b16 v96, v0 offset:8496
	v_or_b32_e32 v4, 2, v68
	s_waitcnt lgkmcnt(0)
	v_ashrrev_i32_e32 v5, 31, v4
	ds_read_b128 v[0:3], v128
	v_mad_i64_i32 v[6:7], s[0:1], v71, s23, v[4:5]
	v_lshlrev_b64 v[6:7], 10, v[6:7]
	v_lshl_add_u64 v[6:7], s[66:67], 0, v[6:7]
	v_lshl_add_u64 v[6:7], v[6:7], 0, v[176:177]
	v_lshl_add_u64 v[8:9], v[6:7], 0, v[66:67]
	s_waitcnt lgkmcnt(0)
	global_store_dwordx4 v[8:9], v[0:3], off
	ds_read_b128 v[0:3], v128 offset:2304
	v_lshl_add_u64 v[6:7], v[6:7], 0, v[64:65]
	v_mad_i64_i32 v[4:5], s[0:1], v70, s23, v[4:5]
	v_lshlrev_b64 v[4:5], 10, v[4:5]
	s_waitcnt lgkmcnt(0)
	global_store_dwordx4 v[6:7], v[0:3], off
	ds_read_b128 v[0:3], v128 offset:4608
	v_lshl_add_u64 v[4:5], s[66:67], 0, v[4:5]
	v_lshl_add_u64 v[4:5], v[4:5], 0, v[176:177]
	v_lshl_add_u64 v[6:7], v[4:5], 0, v[66:67]
	v_lshl_add_u64 v[4:5], v[4:5], 0, v[64:65]
	s_waitcnt lgkmcnt(0)
	global_store_dwordx4 v[6:7], v[0:3], off
	ds_read_b128 v[0:3], v128 offset:6912
	v_readlane_b32 s0, v254, 11
	s_add_i32 s2, s2, s0
	s_cmp_lt_i32 s2, s3
	s_waitcnt lgkmcnt(0)
	global_store_dwordx4 v[4:5], v[0:3], off
	s_waitcnt lgkmcnt(0)
	s_barrier
	s_cbranch_scc1 .LBB0_1031
